# dilated-attention item loop: the first item's Q loads are waited before the loop so the compute no longer waits on the next item's prefetch loads; dropped a redundant store-ack wait before the K/V sta
# baseline (speedup 1.0000x reference)
.LBB0_523:
	s_or_b64 exec, exec, s[26:27]
	s_add_u32 s64, s78, 0xda00000
	s_addc_u32 s65, s79, 0
	s_add_i32 s40, 0, 0x11000
	s_add_u32 s66, s78, 0x1da00000
	s_addc_u32 s67, s79, 0
	s_add_u32 s90, s78, 0x20a00000
	s_addc_u32 s91, s79, 0
	s_and_b64 s[26:27], s[38:39], exec
	s_cselect_b32 s1, 4, 6
	s_and_b64 s[26:27], s[44:45], exec
	s_cselect_b32 s1, s1, 8
	s_ashr_i32 s26, s34, 2
	s_and_b32 s26, s26, -16
	v_and_b32_e32 v146, 15, v224
	s_add_i32 s37, s37, s26
	v_or_b32_e32 v3, s37, v146
	v_lshlrev_b32_e32 v3, s35, v3
	v_add_u32_e32 v68, s36, v3
	v_ashrrev_i32_e32 v69, 31, v68
	v_lshl_add_u64 v[68:69], s[22:23], 0, v[68:69]
	v_mov_b64_e32 v[70:71], s[64:65]
	s_movk_i32 s26, 0xc00
	v_lshrrev_b32_e32 v1, 1, v224
	v_mad_u64_u32 v[70:71], s[22:23], v68, s26, v[70:71]
	v_and_b32_e32 v2, 24, v1
	v_mad_i32_i24 v71, v69, s26, v71
	v_lshl_add_u64 v[68:69], s[4:5], 1, v[70:71]
	v_lshlrev_b32_e32 v70, 1, v2
	v_mov_b32_e32 v71, v0
	v_lshl_add_u64 v[68:69], v[68:69], 0, v[70:71]
	global_load_dwordx4 v[96:99], v[68:69], off
	global_load_dwordx4 v[92:95], v[68:69], off offset:64
	global_load_dwordx4 v[88:91], v[68:69], off offset:128
	global_load_dwordx4 v[84:87], v[68:69], off offset:192
	v_mov_b32_e32 v3, s40
	s_movk_i32 s4, 0x1080
	v_mad_u32_u24 v147, v146, s4, v3
	v_and_b32_e32 v68, 48, v224
	s_movk_i32 s4, 0x210
	v_and_b32_e32 v159, 63, v224
	v_lshlrev_b32_e32 v148, 3, v146
	v_add_u32_e32 v134, 0, v68
	v_lshrrev_b32_e32 v68, 2, v224
	v_mad_u32_u24 v151, v146, s4, v3
	v_lshlrev_b32_e32 v3, 1, v135
	v_lshlrev_b32_e32 v69, 1, v137
	v_lshlrev_b32_e32 v71, 1, v140
	v_lshlrev_b32_e32 v73, 1, v141
	s_and_b64 s[26:27], s[38:39], exec
	v_lshl_add_u32 v132, v146, 4, 0
	v_and_b32_e32 v136, 12, v68
	v_lshlrev_b32_e32 v160, 2, v159
	v_and_b32_e32 v150, 4, v1
	v_mul_lo_u32 v1, v135, s55
	v_xor_b32_e32 v3, v3, v148
	v_mul_lo_u32 v68, v137, s55
	v_xor_b32_e32 v69, v69, v148
	v_mul_lo_u32 v70, v140, s55
	v_xor_b32_e32 v71, v71, v148
	v_mul_lo_u32 v72, v141, s55
	v_xor_b32_e32 v73, v73, v148
	s_cselect_b32 s34, 6, 7
	s_and_b64 s[26:27], s[44:45], exec
	v_cmp_ge_u32_e64 s[22:23], v136, v146
	v_xor_b32_e32 v149, 64, v160
	v_xor_b32_e32 v158, 0x80, v160
	v_cmp_gt_u32_e64 s[4:5], 16, v159
	s_cselect_b32 s34, s34, 6
	s_mov_b32 s37, 0
	v_add_u32_e32 v152, v132, v1
	v_add_u32_e32 v153, v147, v3
	v_add_u32_e32 v154, v132, v68
	v_add_u32_e32 v155, v147, v69
	v_add_u32_e32 v156, v132, v70
	v_add_u32_e32 v157, v147, v71
	v_add_u32_e32 v161, v132, v72
	v_add_u32_e32 v162, v147, v73
	v_lshlrev_b32_e32 v138, 1, v2
	s_waitcnt vmcnt(0)
	s_branch .LBB0_525

.LBB0_527:
	s_and_b32 s40, s37, 1
	s_lshl_b32 s36, s40, 7
	v_xor_b32_e32 v1, s36, v142
	v_mad_u64_u32 v[2:3], s[26:27], v1, s55, v[132:133]
	v_lshlrev_b32_e32 v1, 1, v1
	v_xad_u32 v1, v1, v148, v147
	ds_write_b128 v2, v[36:39]
	ds_write_b16 v1, v40
	ds_write_b16_d16_hi v1, v40 offset:528
	ds_write_b16 v1, v41 offset:1056
	ds_write_b16_d16_hi v1, v41 offset:1584
	ds_write_b16 v1, v42 offset:2112
	ds_write_b16_d16_hi v1, v42 offset:2640
	ds_write_b16 v1, v43 offset:3168
	ds_write_b16_d16_hi v1, v43 offset:3696
	v_xor_b32_e32 v1, s36, v143
	v_mad_u64_u32 v[2:3], s[26:27], v1, s55, v[132:133]
	v_lshlrev_b32_e32 v1, 1, v1
	v_xad_u32 v1, v1, v148, v147
	ds_write_b128 v2, v[48:51]
	ds_write_b16 v1, v44
	ds_write_b16_d16_hi v1, v44 offset:528
	ds_write_b16 v1, v45 offset:1056
	ds_write_b16_d16_hi v1, v45 offset:1584
	ds_write_b16 v1, v46 offset:2112
	ds_write_b16_d16_hi v1, v46 offset:2640
	ds_write_b16 v1, v47 offset:3168
	ds_write_b16_d16_hi v1, v47 offset:3696
	v_xor_b32_e32 v1, s36, v144
	v_mad_u64_u32 v[2:3], s[26:27], v1, s55, v[132:133]
	v_lshlrev_b32_e32 v1, 1, v1
	v_xad_u32 v1, v1, v148, v147
	ds_write_b128 v2, v[52:55]
	ds_write_b16 v1, v56
	ds_write_b16_d16_hi v1, v56 offset:528
	ds_write_b16 v1, v57 offset:1056
	ds_write_b16_d16_hi v1, v57 offset:1584
	ds_write_b16 v1, v58 offset:2112
	ds_write_b16_d16_hi v1, v58 offset:2640
	ds_write_b16 v1, v59 offset:3168
	ds_write_b16_d16_hi v1, v59 offset:3696
	v_xor_b32_e32 v1, s36, v145
	v_mad_u64_u32 v[2:3], s[26:27], v1, s55, v[132:133]
	v_lshlrev_b32_e32 v1, 1, v1
	s_add_i32 s35, s37, 1
	v_xad_u32 v1, v1, v148, v147
	s_cmp_ge_u32 s35, s1
	ds_write_b128 v2, v[64:67]
	ds_write_b16 v1, v60
	ds_write_b16_d16_hi v1, v60 offset:528
	ds_write_b16 v1, v61 offset:1056
	ds_write_b16_d16_hi v1, v61 offset:1584
	ds_write_b16 v1, v62 offset:2112
	ds_write_b16_d16_hi v1, v62 offset:2640
	ds_write_b16 v1, v63 offset:3168
	ds_write_b16_d16_hi v1, v63 offset:3696
	s_waitcnt lgkmcnt(0)
	s_barrier
	s_cbranch_scc1 .LBB0_547
	s_lshr_b32 s26, s35, 1
	s_lshl_b32 s26, s26, s34
	s_add_i32 s26, s26, s0
	s_mul_hi_i32 s27, s26, 0x2aaaaaab
	s_lshr_b32 s48, s27, 31
	s_ashr_i32 s27, s27, 6
	s_add_i32 s27, s27, s48
	s_mul_i32 s48, s27, 0x180
	s_sub_i32 s26, s26, s48
	s_ashr_i32 s48, s26, 7
	s_and_b32 s49, s26, 31
	s_lshl_b32 s50, s48, 1
	s_mulk_i32 s27, 0x300
	s_lshl_b32 s48, s48, 8
	s_lshl_b32 s26, s26, 1
	s_add_i32 s48, s48, s27
	s_and_b32 s26, s26, 0xc0
	s_lshr_b32 s27, s49, s50
	s_or_b32 s26, s48, s26
	s_lshl_b32 s27, s27, 1
	s_and_b32 s48, s35, 1
	s_or_b32 s27, s27, s48
	s_lshl_b32 s48, -1, s50
	s_lshl_b32 s27, s27, s50
	s_andn2_b32 s48, s49, s48
	s_or_b32 s27, s27, s48
	s_add_i32 s27, s26, s27
	s_mul_hi_i32 s26, s27, 0x2aaaaaab
	s_lshr_b32 s48, s26, 31
	s_ashr_i32 s26, s26, 7
	s_add_i32 s26, s26, s48
	s_mul_i32 s48, s26, 0x300
	s_sub_i32 s50, s27, s48
	s_ashr_i32 s51, s50, 8
	s_lshl_b32 s53, s51, 1
	s_and_b32 s27, s50, 63
	s_lshl_b32 s48, -1, s53
	s_andn2_b32 s54, s27, s48
	s_lshr_b32 s56, s27, s53
	s_ashr_i32 s27, s26, 31
	s_lshl_b64 s[48:49], s[26:27], 13
	s_lshl_b32 s27, s50, 1
	s_lshl_b32 s26, s51, 9
	s_and_b32 s27, s27, 0x180
	s_or_b32 s26, s26, s27
	s_bitcmp1_b32 s35, 0
	s_cselect_b64 s[74:75], -1, 0
	s_cmp_lg_u32 s56, 0
	s_cselect_b64 s[50:51], -1, 0
	s_lshl_b32 s56, s56, 7
	s_ashr_i32 s27, s26, 31
	v_readfirstlane_b32 s52, v224
	s_add_i32 s57, s56, 0xffffff80
	v_mov_b32_e32 v69, s27
	v_or_b32_e32 v68, s26, v133
	s_and_b64 vcc, exec, s[74:75]
	s_cbranch_vccnz .LBB0_538
	v_mov_b32_e32 v2, v0
	v_mov_b32_e32 v3, v0
	v_mov_b32_e32 v6, v0
	v_mov_b32_e32 v7, v0
	v_mov_b32_e32 v1, v0
	v_mov_b32_e32 v4, v0
	v_mov_b32_e32 v5, v0
	v_mov_b64_e32 v[10:11], v[6:7]
	v_mov_b64_e32 v[14:15], v[2:3]
	s_or_b64 s[92:93], s[6:7], s[50:51]
	v_mov_b64_e32 v[8:9], v[4:5]
	v_mov_b64_e32 v[12:13], v[0:1]
	s_and_saveexec_b64 s[74:75], s[92:93]
	s_cbranch_execz .LBB0_531
	v_add_u32_e32 v1, s57, v135
	v_lshlrev_b32_e32 v1, s53, v1
	v_add_u32_e32 v2, s54, v1
	v_ashrrev_i32_e32 v3, 31, v2
	v_lshl_add_u64 v[2:3], s[48:49], 0, v[2:3]
	s_movk_i32 s77, 0x600
	v_mad_u64_u32 v[8:9], s[92:93], v2, s77, v[68:69]
	v_mad_i32_i24 v9, v3, s77, v9
	v_lshlrev_b64 v[2:3], 1, v[8:9]
	v_lshl_add_u64 v[8:9], s[60:61], 0, v[2:3]
	v_lshl_add_u64 v[2:3], s[46:47], 0, v[2:3]
	global_load_dwordx4 v[8:11], v[8:9], off
	s_nop 0
	global_load_dwordx4 v[12:15], v[2:3], off

.LBB0_548:
	s_lshr_b32 s26, s37, 1
	s_lshl_b32 s26, s26, s34
	s_add_i32 s26, s26, s0
	s_mul_hi_i32 s27, s26, 0x2aaaaaab
	s_lshr_b32 s37, s27, 31
	s_ashr_i32 s27, s27, 6
	s_add_i32 s27, s27, s37
	s_mul_i32 s37, s27, 0x180
	s_sub_i32 s26, s26, s37
	s_ashr_i32 s37, s26, 7
	s_and_b32 s48, s26, 31
	s_lshl_b32 s49, s37, 1
	s_mulk_i32 s27, 0x300
	s_lshl_b32 s37, s37, 8
	s_add_i32 s37, s37, s27
	s_lshl_b32 s26, s26, 1
	s_lshr_b32 s27, s48, s49
	s_and_b32 s26, s26, 0xc0
	s_lshl_b32 s27, s27, 1
	s_or_b32 s26, s37, s26
	s_or_b32 s27, s27, s40
	s_lshl_b32 s37, -1, s49
	s_lshl_b32 s27, s27, s49
	s_andn2_b32 s37, s48, s37
	s_or_b32 s27, s27, s37
	s_add_i32 s27, s26, s27
	s_mul_hi_i32 s26, s27, 0x2aaaaaab
	s_lshr_b32 s37, s26, 31
	s_ashr_i32 s26, s26, 7
	s_add_i32 s26, s26, s37
	s_mul_i32 s37, s26, 0x300
	s_sub_i32 s37, s27, s37
	s_ashr_i32 s92, s37, 8
	v_readfirstlane_b32 s49, v224
	s_and_b32 s40, s37, 63
	s_lshl_b32 s51, s92, 1
	s_lshr_b32 s48, s40, s51
	s_ashr_i32 s49, s49, 2
	s_lshl_b32 s53, s48, 7
	s_and_b32 s52, s49, -16
	s_add_i32 s49, s52, s53
	v_or_b32_e32 v1, s49, v146
	v_or_b32_e32 v166, s52, v146
	v_lshlrev_b32_e32 v164, s51, v1
	v_xor_b32_e32 v1, s36, v166
	v_mad_u64_u32 v[2:3], s[56:57], v1, s55, v[134:135]
	ds_read_b128 v[100:103], v2
	ds_read_b128 v[104:107], v2 offset:64
	s_waitcnt lgkmcnt(1)
	v_mfma_f32_16x16x32_bf16 v[100:103], v[100:103], v[96:99], 0
	s_lshl_b32 s50, -1, s51
	s_add_i32 s51, s52, 16
	v_mov_b32_e32 v1, s36
	s_waitcnt lgkmcnt(0)
	v_mfma_f32_16x16x32_bf16 v[100:103], v[104:107], v[92:95], v[100:103]
	ds_read_b128 v[104:107], v2 offset:128
	s_add_i32 s53, s52, 32
	s_add_i32 s54, s52, 48
	s_waitcnt lgkmcnt(0)
	v_mfma_f32_16x16x32_bf16 v[100:103], v[104:107], v[88:91], v[100:103]
	ds_read_b128 v[104:107], v2 offset:192
	v_bitop3_b32 v2, s51, v1, v146 bitop3:0x36
	v_mad_u64_u32 v[2:3], s[56:57], v2, s55, v[134:135]
	s_waitcnt lgkmcnt(0)
	v_mfma_f32_16x16x32_bf16 v[100:103], v[104:107], v[84:87], v[100:103]
	ds_read_b128 v[104:107], v2
	ds_read_b128 v[108:111], v2 offset:64
	s_add_i32 s77, s52, 0x80
	s_waitcnt lgkmcnt(1)
	v_mfma_f32_16x16x32_bf16 v[104:107], v[104:107], v[96:99], 0
	s_ashr_i32 s27, s26, 31
	s_bfe_u32 s37, s37, 0x20006
	v_or_b32_e32 v172, s52, v136
	s_waitcnt lgkmcnt(0)
	v_mfma_f32_16x16x32_bf16 v[104:107], v[108:111], v[92:95], v[104:107]
	ds_read_b128 v[108:111], v2 offset:128
	v_or_b32_e32 v173, s51, v136
	v_or_b32_e32 v163, s53, v136
	s_waitcnt lgkmcnt(0)
	v_mfma_f32_16x16x32_bf16 v[104:107], v[108:111], v[88:91], v[104:107]
	ds_read_b128 v[108:111], v2 offset:192
	v_bitop3_b32 v2, s53, v1, v146 bitop3:0x36
	v_mad_u64_u32 v[2:3], s[56:57], v2, s55, v[134:135]
	s_waitcnt lgkmcnt(0)
	v_mfma_f32_16x16x32_bf16 v[104:107], v[108:111], v[84:87], v[104:107]
	ds_read_b128 v[108:111], v2
	ds_read_b128 v[112:115], v2 offset:64
	v_or_b32_e32 v165, s54, v136
	s_waitcnt lgkmcnt(1)
	v_mfma_f32_16x16x32_bf16 v[108:111], v[108:111], v[96:99], 0
	s_waitcnt lgkmcnt(0)
	v_mfma_f32_16x16x32_bf16 v[108:111], v[112:115], v[92:95], v[108:111]
	ds_read_b128 v[112:115], v2 offset:128
	s_waitcnt lgkmcnt(0)
	v_mfma_f32_16x16x32_bf16 v[108:111], v[112:115], v[88:91], v[108:111]
	ds_read_b128 v[112:115], v2 offset:192
	v_bitop3_b32 v2, s54, v1, v146 bitop3:0x36
	v_mad_u64_u32 v[2:3], s[56:57], v2, s55, v[134:135]
	s_waitcnt lgkmcnt(0)
	v_mfma_f32_16x16x32_bf16 v[108:111], v[112:115], v[84:87], v[108:111]
	ds_read_b128 v[112:115], v2
	ds_read_b128 v[116:119], v2 offset:64
	s_add_i32 s56, s52, 64
	s_waitcnt lgkmcnt(1)
	v_mfma_f32_16x16x32_bf16 v[112:115], v[112:115], v[96:99], 0
	s_add_i32 s57, s52, 0x50
	v_or_b32_e32 v139, s57, v136
	s_waitcnt lgkmcnt(0)
	v_mfma_f32_16x16x32_bf16 v[112:115], v[116:119], v[92:95], v[112:115]
	ds_read_b128 v[116:119], v2 offset:128
	s_waitcnt lgkmcnt(0)
	v_mfma_f32_16x16x32_bf16 v[112:115], v[116:119], v[88:91], v[112:115]
	ds_read_b128 v[116:119], v2 offset:192
	v_bitop3_b32 v2, s56, v1, v146 bitop3:0x36
	v_mad_u64_u32 v[2:3], s[74:75], v2, s55, v[134:135]
	s_waitcnt lgkmcnt(0)
	v_mfma_f32_16x16x32_bf16 v[112:115], v[116:119], v[84:87], v[112:115]
	ds_read_b128 v[116:119], v2
	ds_read_b128 v[120:123], v2 offset:64
	s_waitcnt lgkmcnt(1)
	v_mfma_f32_16x16x32_bf16 v[116:119], v[116:119], v[96:99], 0
	s_waitcnt lgkmcnt(0)
	v_mfma_f32_16x16x32_bf16 v[116:119], v[120:123], v[92:95], v[116:119]
	ds_read_b128 v[120:123], v2 offset:128
	s_waitcnt lgkmcnt(0)
	v_mfma_f32_16x16x32_bf16 v[116:119], v[120:123], v[88:91], v[116:119]
	ds_read_b128 v[120:123], v2 offset:192
	v_bitop3_b32 v2, s57, v1, v146 bitop3:0x36
	v_mad_u64_u32 v[2:3], s[74:75], v2, s55, v[134:135]
	s_waitcnt lgkmcnt(0)
	v_mfma_f32_16x16x32_bf16 v[116:119], v[120:123], v[84:87], v[116:119]
	ds_read_b128 v[120:123], v2
	ds_read_b128 v[124:127], v2 offset:64
	s_add_i32 s74, s52, 0x60
	s_waitcnt lgkmcnt(1)
	v_mfma_f32_16x16x32_bf16 v[120:123], v[120:123], v[96:99], 0
	s_add_i32 s75, s52, 0x70
	s_waitcnt lgkmcnt(0)
	v_mfma_f32_16x16x32_bf16 v[120:123], v[124:127], v[92:95], v[120:123]
	ds_read_b128 v[124:127], v2 offset:128
	s_waitcnt lgkmcnt(0)
	v_mfma_f32_16x16x32_bf16 v[120:123], v[124:127], v[88:91], v[120:123]
	ds_read_b128 v[124:127], v2 offset:192
	v_bitop3_b32 v2, s74, v1, v146 bitop3:0x36
	v_mad_u64_u32 v[2:3], s[94:95], v2, s55, v[134:135]
	s_waitcnt lgkmcnt(0)
	v_mfma_f32_16x16x32_bf16 v[120:123], v[124:127], v[84:87], v[120:123]
	ds_read_b128 v[124:127], v2
	ds_read_b128 v[128:131], v2 offset:64
	s_waitcnt lgkmcnt(1)
	v_mfma_f32_16x16x32_bf16 v[124:127], v[124:127], v[96:99], 0
	s_waitcnt lgkmcnt(0)
	v_mfma_f32_16x16x32_bf16 v[124:127], v[128:131], v[92:95], v[124:127]
	ds_read_b128 v[128:131], v2 offset:128
	s_waitcnt lgkmcnt(0)
	v_mfma_f32_16x16x32_bf16 v[124:127], v[128:131], v[88:91], v[124:127]
	ds_read_b128 v[128:131], v2 offset:192
	v_bitop3_b32 v2, s75, v1, v146 bitop3:0x36
	v_mad_u64_u32 v[2:3], s[94:95], v2, s55, v[134:135]
	s_waitcnt lgkmcnt(0)
	v_mfma_f32_16x16x32_bf16 v[124:127], v[128:131], v[84:87], v[124:127]
	ds_read_b128 v[128:131], v2
	ds_read_b128 v[168:171], v2 offset:64
	v_bitop3_b32 v1, s77, v1, v146 bitop3:0x36
	s_waitcnt lgkmcnt(1)
	v_mfma_f32_16x16x32_bf16 v[128:131], v[128:131], v[96:99], 0
	s_waitcnt lgkmcnt(0)
	v_mfma_f32_16x16x32_bf16 v[128:131], v[168:171], v[92:95], v[128:131]
	ds_read_b128 v[168:171], v2 offset:128
	s_waitcnt lgkmcnt(0)
	v_mfma_f32_16x16x32_bf16 v[128:131], v[168:171], v[88:91], v[128:131]
	ds_read_b128 v[168:171], v2 offset:192
	v_mad_u64_u32 v[2:3], s[94:95], v1, s55, v[134:135]
	s_waitcnt lgkmcnt(0)
	v_mfma_f32_16x16x32_bf16 v[128:131], v[168:171], v[84:87], v[128:131]
	ds_read_b128 v[168:171], v2
	s_lshl_b64 s[94:95], s[26:27], 13
	s_cmp_lg_u32 s48, 0
	s_waitcnt lgkmcnt(0)
	v_mfma_f32_16x16x32_bf16 v[96:99], v[168:171], v[96:99], 0
	ds_read_b128 v[168:171], v2 offset:64
	s_cselect_b64 s[48:49], -1, 0
	v_or_b32_e32 v1, 1, v172
	s_waitcnt lgkmcnt(0)
	v_mfma_f32_16x16x32_bf16 v[92:95], v[168:171], v[92:95], v[96:99]
	s_nop 2
	ds_read_b128 v[96:99], v2 offset:128
	v_or_b32_e32 v3, s56, v136
	s_ashr_i32 s93, s92, 31
	s_waitcnt lgkmcnt(0)
	v_mfma_f32_16x16x32_bf16 v[88:91], v[96:99], v[88:91], v[92:95]
	s_nop 2
	ds_read_b128 v[92:95], v2 offset:192
	v_or_b32_e32 v2, 2, v172
	s_waitcnt lgkmcnt(0)
	v_mfma_f32_16x16x32_bf16 v[84:87], v[92:95], v[84:87], v[88:91]
	s_nop 2
	v_add_u32_e32 v88, 0x80, v166
	v_cmp_le_i32_e32 vcc, v172, v88
	s_and_b64 s[26:27], s[22:23], vcc
	v_cmp_lt_i32_e32 vcc, s25, v172
	s_or_b64 vcc, s[48:49], vcc
	s_and_b64 vcc, s[26:27], vcc
	v_cndmask_b32_e32 v89, v239, v100, vcc
	v_cmp_ge_i32_e32 vcc, v1, v166
	v_cmp_lt_i32_e64 s[26:27], v172, v88
	s_and_b64 s[26:27], vcc, s[26:27]
	v_cmp_lt_i32_e32 vcc, s88, v172
	s_or_b64 vcc, s[48:49], vcc
	s_and_b64 vcc, s[26:27], vcc
	v_cndmask_b32_e32 v90, v239, v101, vcc
	s_mov_b32 s26, 0xff800000
	v_max3_f32 v1, v89, s26, v90
	v_cmp_ge_i32_e32 vcc, v2, v166
	v_cmp_le_i32_e64 s[26:27], v2, v88
	s_and_b64 s[26:27], vcc, s[26:27]
	v_cmp_lt_i32_e32 vcc, s25, v2
	s_or_b64 vcc, s[48:49], vcc
	s_and_b64 vcc, s[26:27], vcc
	v_or_b32_e32 v2, 3, v172
	v_cndmask_b32_e32 v91, v239, v102, vcc
	v_cmp_ge_i32_e32 vcc, v2, v166
	v_cmp_le_i32_e64 s[26:27], v2, v88
	s_and_b64 s[26:27], vcc, s[26:27]
	v_cmp_lt_i32_e32 vcc, s25, v2
	s_or_b64 vcc, s[48:49], vcc
	s_and_b64 vcc, s[26:27], vcc
	v_cndmask_b32_e32 v92, v239, v103, vcc
	v_cmp_ge_i32_e32 vcc, v173, v166
	v_cmp_le_i32_e64 s[26:27], v173, v88
	s_and_b64 s[26:27], vcc, s[26:27]
	v_cmp_lt_i32_e32 vcc, s25, v173
	s_or_b64 vcc, s[48:49], vcc
	s_and_b64 vcc, s[26:27], vcc
	v_or_b32_e32 v2, 1, v173
	v_cndmask_b32_e32 v93, v239, v104, vcc
	v_cmp_ge_i32_e32 vcc, v2, v166
	v_cmp_lt_i32_e64 s[26:27], v173, v88
	s_and_b64 s[26:27], vcc, s[26:27]
	v_cmp_lt_i32_e32 vcc, s88, v173
	s_or_b64 vcc, s[48:49], vcc
	s_and_b64 vcc, s[26:27], vcc
	v_or_b32_e32 v2, 2, v173
	v_cndmask_b32_e32 v94, v239, v105, vcc
	v_cmp_ge_i32_e32 vcc, v2, v166
	v_cmp_le_i32_e64 s[26:27], v2, v88
	s_and_b64 s[26:27], vcc, s[26:27]
	v_cmp_lt_i32_e32 vcc, s25, v2
	s_or_b64 vcc, s[48:49], vcc
	s_and_b64 vcc, s[26:27], vcc
	v_or_b32_e32 v2, 3, v173
	v_cndmask_b32_e32 v95, v239, v106, vcc
	v_cmp_ge_i32_e32 vcc, v2, v166
	v_cmp_le_i32_e64 s[26:27], v2, v88
	s_and_b64 s[26:27], vcc, s[26:27]
	v_cmp_lt_i32_e32 vcc, s25, v2
	s_or_b64 vcc, s[48:49], vcc
	s_and_b64 vcc, s[26:27], vcc
	v_cndmask_b32_e32 v96, v239, v107, vcc
	v_cmp_ge_i32_e32 vcc, v163, v166
	v_cmp_le_i32_e64 s[26:27], v163, v88
	s_and_b64 s[26:27], vcc, s[26:27]
	v_cmp_lt_i32_e32 vcc, s25, v163
	s_or_b64 s[52:53], s[48:49], vcc
	s_and_b64 vcc, s[26:27], s[52:53]
	v_or_b32_e32 v2, 1, v163
	v_cndmask_b32_e32 v97, v239, v108, vcc
	v_cmp_ge_i32_e32 vcc, v2, v166
	v_cmp_lt_i32_e64 s[26:27], v163, v88
	s_and_b64 s[26:27], vcc, s[26:27]
	v_cmp_lt_i32_e32 vcc, s88, v163
	s_or_b64 s[52:53], s[48:49], vcc
	s_and_b64 vcc, s[26:27], s[52:53]
	v_or_b32_e32 v2, 2, v163
	v_cndmask_b32_e32 v98, v239, v109, vcc
	v_cmp_ge_i32_e32 vcc, v2, v166
	v_cmp_le_i32_e64 s[26:27], v2, v88
	s_and_b64 s[26:27], vcc, s[26:27]
	v_cmp_lt_i32_e32 vcc, s25, v2
	s_or_b64 s[52:53], s[48:49], vcc
	s_and_b64 vcc, s[26:27], s[52:53]
	v_or_b32_e32 v2, 3, v163
	v_cndmask_b32_e32 v99, v239, v110, vcc
	v_cmp_ge_i32_e32 vcc, v2, v166
	v_cmp_le_i32_e64 s[26:27], v2, v88
	s_and_b64 s[26:27], vcc, s[26:27]
	v_cmp_lt_i32_e32 vcc, s25, v2
	s_or_b64 s[52:53], s[48:49], vcc
	s_and_b64 vcc, s[26:27], s[52:53]
	v_cndmask_b32_e32 v100, v239, v111, vcc
	v_cmp_ge_i32_e32 vcc, v165, v166
	v_cmp_le_i32_e64 s[26:27], v165, v88
	s_and_b64 s[26:27], vcc, s[26:27]
	v_cmp_lt_i32_e32 vcc, s25, v165
	s_or_b64 s[52:53], s[48:49], vcc
	s_and_b64 vcc, s[26:27], s[52:53]
	v_or_b32_e32 v2, 1, v165
	v_cndmask_b32_e32 v101, v239, v112, vcc
	v_cmp_ge_i32_e32 vcc, v2, v166
	v_cmp_lt_i32_e64 s[26:27], v165, v88
	s_and_b64 s[26:27], vcc, s[26:27]
	v_cmp_lt_i32_e32 vcc, s88, v165
	s_or_b64 s[52:53], s[48:49], vcc
	s_and_b64 vcc, s[26:27], s[52:53]
	v_or_b32_e32 v2, 2, v165
	v_cndmask_b32_e32 v102, v239, v113, vcc
	v_cmp_ge_i32_e32 vcc, v2, v166
	v_cmp_le_i32_e64 s[26:27], v2, v88
	s_and_b64 s[26:27], vcc, s[26:27]
	v_cmp_lt_i32_e32 vcc, s25, v2
	s_or_b64 s[52:53], s[48:49], vcc
	s_and_b64 vcc, s[26:27], s[52:53]
	v_or_b32_e32 v2, 3, v165
	v_cndmask_b32_e32 v103, v239, v114, vcc
	v_cmp_ge_i32_e32 vcc, v2, v166
	v_cmp_le_i32_e64 s[26:27], v2, v88
	s_and_b64 s[26:27], vcc, s[26:27]
	v_cmp_lt_i32_e32 vcc, s25, v2
	s_or_b64 s[52:53], s[48:49], vcc
	s_and_b64 vcc, s[26:27], s[52:53]
	v_cndmask_b32_e32 v104, v239, v115, vcc
	v_cmp_ge_i32_e32 vcc, v3, v166
	v_cmp_le_i32_e64 s[26:27], v3, v88
	s_and_b64 s[26:27], vcc, s[26:27]
	v_cmp_lt_i32_e32 vcc, s25, v3
	s_or_b64 s[52:53], s[48:49], vcc
	s_and_b64 vcc, s[26:27], s[52:53]
	v_or_b32_e32 v2, 1, v3
	v_cndmask_b32_e32 v105, v239, v116, vcc
	v_cmp_ge_i32_e32 vcc, v2, v166
	v_cmp_lt_i32_e64 s[26:27], v3, v88
	s_and_b64 s[26:27], vcc, s[26:27]
	v_cmp_lt_i32_e32 vcc, s88, v3
	s_or_b64 s[52:53], s[48:49], vcc
	s_and_b64 vcc, s[26:27], s[52:53]
	v_or_b32_e32 v2, 2, v3
	v_cndmask_b32_e32 v106, v239, v117, vcc
	v_cmp_ge_i32_e32 vcc, v2, v166
	v_cmp_le_i32_e64 s[26:27], v2, v88
	s_and_b64 s[26:27], vcc, s[26:27]
	v_cmp_lt_i32_e32 vcc, s25, v2
	s_or_b64 s[52:53], s[48:49], vcc
	s_and_b64 vcc, s[26:27], s[52:53]
	v_or_b32_e32 v2, 3, v3
	v_cndmask_b32_e32 v107, v239, v118, vcc
	v_cmp_ge_i32_e32 vcc, v2, v166
	v_cmp_le_i32_e64 s[26:27], v2, v88
	s_and_b64 s[26:27], vcc, s[26:27]
	v_cmp_lt_i32_e32 vcc, s25, v2
	s_or_b64 s[52:53], s[48:49], vcc
	s_and_b64 vcc, s[26:27], s[52:53]
	v_cndmask_b32_e32 v108, v239, v119, vcc
	v_cmp_ge_i32_e32 vcc, v139, v166
	v_cmp_le_i32_e64 s[26:27], v139, v88
	s_and_b64 s[26:27], vcc, s[26:27]
	v_cmp_lt_i32_e32 vcc, s25, v139
	s_or_b64 s[52:53], s[48:49], vcc
	s_and_b64 vcc, s[26:27], s[52:53]
	v_or_b32_e32 v2, 1, v139
	v_cndmask_b32_e32 v109, v239, v120, vcc
	v_cmp_ge_i32_e32 vcc, v2, v166
	v_cmp_lt_i32_e64 s[26:27], v139, v88
	s_and_b64 s[26:27], vcc, s[26:27]
	v_cmp_lt_i32_e32 vcc, s88, v139
	s_or_b64 s[52:53], s[48:49], vcc
	v_max3_f32 v1, v1, v91, v92
	s_and_b64 vcc, s[26:27], s[52:53]
	v_or_b32_e32 v2, 2, v139
	v_max3_f32 v1, v1, v93, v94
	v_cndmask_b32_e32 v110, v239, v121, vcc
	v_cmp_ge_i32_e32 vcc, v2, v166
	v_cmp_le_i32_e64 s[26:27], v2, v88
	v_max3_f32 v1, v1, v95, v96
	s_and_b64 s[26:27], vcc, s[26:27]
	v_cmp_lt_i32_e32 vcc, s25, v2
	v_max3_f32 v1, v1, v97, v98
	s_or_b64 s[52:53], s[48:49], vcc
	v_max3_f32 v1, v1, v99, v100
	s_and_b64 vcc, s[26:27], s[52:53]
	v_or_b32_e32 v2, 3, v139
	v_max3_f32 v1, v1, v101, v102
	v_cndmask_b32_e32 v111, v239, v122, vcc
	v_cmp_ge_i32_e32 vcc, v2, v166
	v_cmp_le_i32_e64 s[26:27], v2, v88
	v_max3_f32 v1, v1, v103, v104
	s_and_b64 s[26:27], vcc, s[26:27]
	v_cmp_lt_i32_e32 vcc, s25, v2
	v_max3_f32 v1, v1, v105, v106
	s_or_b64 s[52:53], s[48:49], vcc
	v_max3_f32 v1, v1, v107, v108
	s_and_b64 vcc, s[26:27], s[52:53]
	v_max3_f32 v1, v1, v109, v110
	v_cndmask_b32_e32 v112, v239, v123, vcc
	v_max3_f32 v2, v1, v111, v112
	v_or_b32_e32 v1, s74, v136
	v_cmp_ge_i32_e32 vcc, v1, v166
	v_cmp_le_i32_e64 s[26:27], v1, v88
	s_and_b64 s[26:27], vcc, s[26:27]
	v_cmp_lt_i32_e32 vcc, s25, v1
	s_or_b64 s[52:53], s[48:49], vcc
	s_and_b64 vcc, s[26:27], s[52:53]
	v_or_b32_e32 v114, 1, v1
	v_cndmask_b32_e32 v113, v239, v124, vcc
	v_cmp_ge_i32_e32 vcc, v114, v166
	v_cmp_lt_i32_e64 s[26:27], v1, v88
	s_and_b64 s[26:27], vcc, s[26:27]
	v_cmp_lt_i32_e32 vcc, s88, v1
	s_or_b64 s[52:53], s[48:49], vcc
	s_and_b64 vcc, s[26:27], s[52:53]
	v_or_b32_e32 v115, 2, v1
	v_cndmask_b32_e32 v114, v239, v125, vcc
	v_cmp_ge_i32_e32 vcc, v115, v166
	v_cmp_le_i32_e64 s[26:27], v115, v88
	s_and_b64 s[26:27], vcc, s[26:27]
	v_cmp_lt_i32_e32 vcc, s25, v115
	s_or_b64 s[52:53], s[48:49], vcc
	s_and_b64 vcc, s[26:27], s[52:53]
	v_or_b32_e32 v116, 3, v1
	v_cndmask_b32_e32 v115, v239, v126, vcc
	v_cmp_ge_i32_e32 vcc, v116, v166
	v_cmp_le_i32_e64 s[26:27], v116, v88
	s_and_b64 s[26:27], vcc, s[26:27]
	v_cmp_lt_i32_e32 vcc, s25, v116
	s_or_b64 s[52:53], s[48:49], vcc
	s_and_b64 vcc, s[26:27], s[52:53]
	v_max3_f32 v2, v2, v113, v114
	v_cndmask_b32_e32 v120, v239, v127, vcc
	v_max3_f32 v116, v2, v115, v120
	v_or_b32_e32 v2, s75, v136
	v_cmp_ge_i32_e32 vcc, v2, v166
	v_cmp_le_i32_e64 s[26:27], v2, v88
	s_and_b64 s[26:27], vcc, s[26:27]
	v_cmp_lt_i32_e32 vcc, s25, v2
	s_or_b64 s[52:53], s[48:49], vcc
	s_and_b64 vcc, s[26:27], s[52:53]
	v_or_b32_e32 v117, 1, v2
	v_cndmask_b32_e32 v123, v239, v128, vcc
	v_cmp_ge_i32_e32 vcc, v117, v166
	v_cmp_lt_i32_e64 s[26:27], v2, v88
	s_and_b64 s[26:27], vcc, s[26:27]
	v_cmp_lt_i32_e32 vcc, s88, v2
	s_or_b64 s[52:53], s[48:49], vcc
	s_and_b64 vcc, s[26:27], s[52:53]
	v_or_b32_e32 v117, 2, v2
	v_cndmask_b32_e32 v124, v239, v129, vcc
	v_cmp_ge_i32_e32 vcc, v117, v166
	v_cmp_le_i32_e64 s[26:27], v117, v88
	s_and_b64 s[26:27], vcc, s[26:27]
	v_cmp_lt_i32_e32 vcc, s25, v117
	s_or_b64 s[52:53], s[48:49], vcc
	s_and_b64 vcc, s[26:27], s[52:53]
	v_or_b32_e32 v117, 3, v2
	v_cndmask_b32_e32 v125, v239, v130, vcc
	v_cmp_ge_i32_e32 vcc, v117, v166
	v_cmp_le_i32_e64 s[26:27], v117, v88
	s_and_b64 s[26:27], vcc, s[26:27]
	v_cmp_lt_i32_e32 vcc, s25, v117
	s_or_b64 s[52:53], s[48:49], vcc
	s_and_b64 vcc, s[26:27], s[52:53]
	v_or_b32_e32 v121, s77, v136
	v_cndmask_b32_e32 v126, v239, v131, vcc
	v_cmp_ge_i32_e32 vcc, v121, v166
	v_cmp_le_i32_e64 s[26:27], v121, v88
	s_and_b64 s[26:27], vcc, s[26:27]
	v_cmp_lt_i32_e32 vcc, s25, v121
	s_or_b64 s[52:53], s[48:49], vcc
	s_and_b64 vcc, s[26:27], s[52:53]
	v_or_b32_e32 v117, 1, v121
	v_cndmask_b32_e32 v84, v239, v84, vcc
	v_cmp_ge_i32_e32 vcc, v117, v166
	v_cmp_lt_i32_e64 s[26:27], v121, v88
	s_and_b64 s[26:27], vcc, s[26:27]
	v_cmp_lt_i32_e32 vcc, s88, v121
	s_or_b64 s[52:53], s[48:49], vcc
	s_and_b64 vcc, s[26:27], s[52:53]
	v_or_b32_e32 v117, 2, v121
	v_cndmask_b32_e32 v85, v239, v85, vcc
	v_cmp_ge_i32_e32 vcc, v117, v166
	v_cmp_le_i32_e64 s[26:27], v117, v88
	s_and_b64 s[26:27], vcc, s[26:27]
	v_cmp_lt_i32_e32 vcc, s25, v117
	s_or_b64 s[52:53], s[48:49], vcc
	s_and_b64 vcc, s[26:27], s[52:53]
	v_or_b32_e32 v117, 3, v121
	v_cndmask_b32_e32 v86, v239, v86, vcc
	v_cmp_ge_i32_e32 vcc, v117, v166
	v_cmp_le_i32_e64 s[26:27], v117, v88
	s_and_b64 s[26:27], vcc, s[26:27]
	v_cmp_lt_i32_e32 vcc, s25, v117
	v_max3_f32 v116, v116, v123, v124
	s_or_b64 s[48:49], s[48:49], vcc
	v_max3_f32 v116, v116, v125, v126
	s_and_b64 vcc, s[26:27], s[48:49]
	v_max3_f32 v116, v116, v84, v85
	v_cndmask_b32_e32 v87, v239, v87, vcc
	v_max3_f32 v88, v116, v86, v87
	ds_bpermute_b32 v116, v149, v88
	s_andn2_b32 s26, s40, s50
	v_or_b32_e32 v129, s36, v150
	s_waitcnt lgkmcnt(0)
	v_max_f32_e32 v116, v116, v116
	v_max_f32_e32 v88, v88, v116
	ds_bpermute_b32 v116, v158, v88
	s_waitcnt lgkmcnt(0)
	v_max_f32_e32 v116, v116, v116
	v_max_f32_e32 v122, v88, v116
	v_sub_f32_e32 v88, v89, v122
	v_exp_f32_e32 v88, v88
	v_sub_f32_e32 v90, v90, v122
	v_exp_f32_e32 v90, v90
	v_sub_f32_e32 v91, v91, v122
	v_exp_f32_e32 v91, v91
	v_sub_f32_e32 v92, v92, v122
	v_exp_f32_e32 v92, v92
	v_sub_f32_e32 v93, v93, v122
	v_add_f32_e32 v89, 0, v88
	v_exp_f32_e32 v93, v93
	v_sub_f32_e32 v94, v94, v122
	v_add_f32_e32 v89, v90, v89
	v_exp_f32_e32 v94, v94
	v_sub_f32_e32 v95, v95, v122
	v_add_f32_e32 v89, v91, v89
	v_exp_f32_e32 v95, v95
	v_sub_f32_e32 v96, v96, v122
	v_add_f32_e32 v89, v92, v89
	v_exp_f32_e32 v96, v96
	v_sub_f32_e32 v97, v97, v122
	v_add_f32_e32 v89, v93, v89
	v_exp_f32_e32 v116, v97
	v_sub_f32_e32 v97, v98, v122
	v_add_f32_e32 v89, v94, v89
	v_exp_f32_e32 v117, v97
	v_sub_f32_e32 v97, v99, v122
	v_add_f32_e32 v89, v95, v89
	v_exp_f32_e32 v118, v97
	v_sub_f32_e32 v97, v100, v122
	v_add_f32_e32 v89, v96, v89
	v_exp_f32_e32 v119, v97
	v_sub_f32_e32 v97, v101, v122
	v_add_f32_e32 v89, v116, v89
	v_exp_f32_e32 v182, v97
	v_sub_f32_e32 v97, v102, v122
	v_add_f32_e32 v89, v117, v89
	v_exp_f32_e32 v183, v97
	v_sub_f32_e32 v97, v103, v122
	v_add_f32_e32 v89, v118, v89
	v_exp_f32_e32 v184, v97
	v_sub_f32_e32 v97, v104, v122
	v_add_f32_e32 v89, v119, v89
	v_exp_f32_e32 v185, v97
	v_sub_f32_e32 v97, v105, v122
	v_add_f32_e32 v89, v182, v89
	v_exp_f32_e32 v174, v97
	v_sub_f32_e32 v97, v106, v122
	v_add_f32_e32 v89, v183, v89
	v_exp_f32_e32 v175, v97
	v_sub_f32_e32 v97, v107, v122
	v_add_f32_e32 v89, v184, v89
	v_exp_f32_e32 v176, v97
	v_sub_f32_e32 v97, v108, v122
	v_add_f32_e32 v89, v185, v89
	v_exp_f32_e32 v177, v97
	v_sub_f32_e32 v97, v109, v122
	v_add_f32_e32 v89, v174, v89
	v_exp_f32_e32 v178, v97
	v_sub_f32_e32 v97, v110, v122
	v_add_f32_e32 v89, v175, v89
	v_exp_f32_e32 v179, v97
	v_sub_f32_e32 v97, v111, v122
	v_add_f32_e32 v89, v176, v89
	v_exp_f32_e32 v180, v97
	v_sub_f32_e32 v97, v112, v122
	v_add_f32_e32 v89, v177, v89
	v_exp_f32_e32 v181, v97
	v_sub_f32_e32 v97, v113, v122
	v_add_f32_e32 v89, v178, v89
	v_exp_f32_e32 v130, v97
	v_sub_f32_e32 v97, v114, v122
	v_add_f32_e32 v89, v179, v89
	v_exp_f32_e32 v131, v97
	v_sub_f32_e32 v97, v115, v122
	v_add_f32_e32 v89, v180, v89
	v_exp_f32_e32 v166, v97
	v_sub_f32_e32 v97, v120, v122
	v_add_f32_e32 v89, v181, v89
	v_exp_f32_e32 v167, v97
	v_sub_f32_e32 v97, v123, v122
	v_add_f32_e32 v89, v130, v89
	v_exp_f32_e32 v168, v97
	v_sub_f32_e32 v97, v124, v122
	v_add_f32_e32 v89, v131, v89
	v_exp_f32_e32 v169, v97
	v_sub_f32_e32 v97, v125, v122
	v_add_f32_e32 v89, v166, v89
	v_exp_f32_e32 v170, v97
	v_sub_f32_e32 v97, v126, v122
	v_add_f32_e32 v89, v167, v89
	v_exp_f32_e32 v171, v97
	v_sub_f32_e32 v84, v84, v122
	v_add_f32_e32 v89, v168, v89
	v_exp_f32_e32 v125, v84
	v_sub_f32_e32 v85, v85, v122
	v_add_f32_e32 v89, v169, v89
	v_exp_f32_e32 v126, v85
	v_sub_f32_e32 v85, v86, v122
	v_add_f32_e32 v89, v170, v89
	v_exp_f32_e32 v127, v85
	v_sub_f32_e32 v85, v87, v122
	v_add_f32_e32 v89, v171, v89
	v_exp_f32_e32 v128, v85
	v_add_f32_e32 v84, v125, v89
	v_add_f32_e32 v84, v126, v84
	v_add_f32_e32 v84, v127, v84
	v_add_f32_e32 v84, v128, v84
	ds_bpermute_b32 v85, v149, v84
	v_add_u32_e32 v120, s26, v164
	v_bitop3_b32 v164, v172, v129, 56 bitop3:0x1e
	v_lshl_add_u32 v164, v164, 1, v151
	v_bitop3_b32 v86, v173, s36, v150 bitop3:0x1e
	s_waitcnt lgkmcnt(0)
	v_add_f32_e32 v123, v84, v85
	v_bitop3_b32 v84, v172, s36, v150 bitop3:0x1e
	ds_read_b64 v[186:187], v164 offset:59136
	v_bitop3_b32 v164, v173, v129, 56 bitop3:0x1e
	v_lshl_add_u32 v84, v84, 1, v151
	v_lshl_add_u32 v86, v86, 1, v151
	v_lshl_add_u32 v164, v164, 1, v151
	ds_read_b64 v[84:85], v84
	ds_read_b64 v[86:87], v86
	ds_read_b64 v[188:189], v164 offset:59136
	v_bitop3_b32 v164, v163, s36, v150 bitop3:0x1e
	v_lshl_add_u32 v164, v164, 1, v151
	v_cvt_pk_bf16_f32 v116, v116, v117
	v_cvt_pk_bf16_f32 v117, v118, v119
	v_cvt_pk_bf16_f32 v118, v182, v183
	ds_read_b64 v[182:183], v164
	v_bitop3_b32 v164, v165, s36, v150 bitop3:0x1e
	v_lshl_add_u32 v164, v164, 1, v151
	v_cvt_pk_bf16_f32 v119, v184, v185
	ds_read_b64 v[184:185], v164
	v_cvt_pk_bf16_f32 v112, v88, v90
	v_bitop3_b32 v88, v172, v129, 8 bitop3:0x1e
	v_bitop3_b32 v90, v173, v129, 8 bitop3:0x1e
	v_cvt_pk_bf16_f32 v113, v91, v92
	v_cvt_pk_bf16_f32 v114, v93, v94
	v_cvt_pk_bf16_f32 v115, v95, v96
	v_lshl_add_u32 v88, v88, 1, v151
	v_lshl_add_u32 v90, v90, 1, v151
	ds_read_b64 v[88:89], v88 offset:8448
	ds_read_b64 v[90:91], v90 offset:8448
	s_waitcnt lgkmcnt(5)
	v_mfma_f32_16x16x32_bf16 v[84:87], v[84:87], v[112:115], 0
	v_bitop3_b32 v164, v163, v129, 8 bitop3:0x1e
	v_lshl_add_u32 v164, v164, 1, v151
	v_bitop3_b32 v92, v172, v129, 16 bitop3:0x1e
	s_waitcnt lgkmcnt(2)
	v_mfma_f32_16x16x32_bf16 v[84:87], v[182:185], v[116:119], v[84:87]
	ds_read_b64 v[182:183], v164 offset:8448
	v_bitop3_b32 v164, v165, v129, 8 bitop3:0x1e
	v_lshl_add_u32 v164, v164, 1, v151
	ds_read_b64 v[184:185], v164 offset:8448
	s_waitcnt lgkmcnt(2)
	v_mfma_f32_16x16x32_bf16 v[88:91], v[88:91], v[112:115], 0
	v_bitop3_b32 v94, v173, v129, 16 bitop3:0x1e
	v_lshl_add_u32 v92, v92, 1, v151
	v_lshl_add_u32 v94, v94, 1, v151
	ds_read_b64 v[92:93], v92 offset:16896
	ds_read_b64 v[94:95], v94 offset:16896
	v_bitop3_b32 v164, v163, v129, 16 bitop3:0x1e
	v_lshl_add_u32 v164, v164, 1, v151
	s_waitcnt lgkmcnt(2)
	v_mfma_f32_16x16x32_bf16 v[88:91], v[182:185], v[116:119], v[88:91]
	ds_read_b64 v[182:183], v164 offset:16896
	v_bitop3_b32 v164, v165, v129, 16 bitop3:0x1e
	v_lshl_add_u32 v164, v164, 1, v151
	ds_read_b64 v[184:185], v164 offset:16896
	v_bitop3_b32 v96, v172, v129, 24 bitop3:0x1e
	v_bitop3_b32 v98, v173, v129, 24 bitop3:0x1e
	v_lshl_add_u32 v96, v96, 1, v151
	v_lshl_add_u32 v98, v98, 1, v151
	ds_read_b64 v[96:97], v96 offset:25344
	ds_read_b64 v[98:99], v98 offset:25344
	s_waitcnt lgkmcnt(4)
	v_mfma_f32_16x16x32_bf16 v[92:95], v[92:95], v[112:115], 0
	v_bitop3_b32 v164, v163, v129, 24 bitop3:0x1e
	v_lshl_add_u32 v164, v164, 1, v151
	v_bitop3_b32 v100, v172, v129, 32 bitop3:0x1e
	s_waitcnt lgkmcnt(2)
	v_mfma_f32_16x16x32_bf16 v[92:95], v[182:185], v[116:119], v[92:95]
	ds_read_b64 v[182:183], v164 offset:25344
	v_bitop3_b32 v164, v165, v129, 24 bitop3:0x1e
	v_lshl_add_u32 v164, v164, 1, v151
	ds_read_b64 v[184:185], v164 offset:25344
	s_waitcnt lgkmcnt(2)
	v_mfma_f32_16x16x32_bf16 v[96:99], v[96:99], v[112:115], 0
	v_bitop3_b32 v102, v173, v129, 32 bitop3:0x1e
	v_lshl_add_u32 v100, v100, 1, v151
	v_lshl_add_u32 v102, v102, 1, v151
	ds_read_b64 v[100:101], v100 offset:33792
	ds_read_b64 v[102:103], v102 offset:33792
	v_bitop3_b32 v108, v172, v129, 48 bitop3:0x1e
	v_bitop3_b32 v110, v173, v129, 48 bitop3:0x1e
	v_bitop3_b32 v164, v163, v129, 32 bitop3:0x1e
	v_lshl_add_u32 v108, v108, 1, v151
	v_lshl_add_u32 v110, v110, 1, v151
	v_lshl_add_u32 v164, v164, 1, v151
	ds_read_b64 v[108:109], v108 offset:50688
	ds_read_b64 v[110:111], v110 offset:50688
	s_waitcnt lgkmcnt(4)
	v_mfma_f32_16x16x32_bf16 v[96:99], v[182:185], v[116:119], v[96:99]
	ds_read_b64 v[182:183], v164 offset:33792
	v_bitop3_b32 v164, v165, v129, 32 bitop3:0x1e
	v_lshl_add_u32 v164, v164, 1, v151
	ds_read_b64 v[184:185], v164 offset:33792
	v_bitop3_b32 v104, v172, v129, 40 bitop3:0x1e
	v_bitop3_b32 v106, v173, v129, 40 bitop3:0x1e
	v_lshl_add_u32 v104, v104, 1, v151
	v_lshl_add_u32 v106, v106, 1, v151
	ds_read_b64 v[104:105], v104 offset:42240
	ds_read_b64 v[106:107], v106 offset:42240
	s_waitcnt lgkmcnt(6)
	v_mfma_f32_16x16x32_bf16 v[100:103], v[100:103], v[112:115], 0
	v_bitop3_b32 v164, v163, v129, 40 bitop3:0x1e
	v_lshl_add_u32 v164, v164, 1, v151
	ds_bpermute_b32 v124, v158, v123
	s_waitcnt lgkmcnt(3)
	v_mfma_f32_16x16x32_bf16 v[100:103], v[182:185], v[116:119], v[100:103]
	ds_read_b64 v[182:183], v164 offset:42240
	v_bitop3_b32 v164, v165, v129, 40 bitop3:0x1e
	v_lshl_add_u32 v164, v164, 1, v151
	ds_read_b64 v[184:185], v164 offset:42240
	s_waitcnt lgkmcnt(3)
	v_mfma_f32_16x16x32_bf16 v[104:107], v[104:107], v[112:115], 0
	v_bitop3_b32 v164, v163, v129, 48 bitop3:0x1e
	v_lshl_add_u32 v164, v164, 1, v151
	v_bitop3_b32 v163, v163, v129, 56 bitop3:0x1e
	s_waitcnt lgkmcnt(0)
	v_mfma_f32_16x16x32_bf16 v[104:107], v[182:185], v[116:119], v[104:107]
	ds_read_b64 v[182:183], v164 offset:50688
	v_bitop3_b32 v164, v165, v129, 48 bitop3:0x1e
	v_lshl_add_u32 v164, v164, 1, v151
	ds_read_b64 v[184:185], v164 offset:50688
	v_mfma_f32_16x16x32_bf16 v[108:111], v[108:111], v[112:115], 0
	v_lshl_add_u32 v163, v163, 1, v151
	s_waitcnt lgkmcnt(0)
	v_mfma_f32_16x16x32_bf16 v[108:111], v[182:185], v[116:119], v[108:111]
	ds_read_b64 v[182:183], v163 offset:59136
	v_bitop3_b32 v163, v165, v129, 56 bitop3:0x1e
	v_lshl_add_u32 v163, v163, 1, v151
	ds_read_b64 v[184:185], v163 offset:59136
	v_mfma_f32_16x16x32_bf16 v[112:115], v[186:189], v[112:115], 0
	v_bitop3_b32 v163, v3, s36, v150 bitop3:0x1e
	v_lshl_add_u32 v163, v163, 1, v151
	ds_read_b64 v[172:173], v163
	v_bitop3_b32 v163, v139, s36, v150 bitop3:0x1e
	v_lshl_add_u32 v163, v163, 1, v151
	s_waitcnt lgkmcnt(1)
	v_mfma_f32_16x16x32_bf16 v[112:115], v[182:185], v[116:119], v[112:115]
	v_cvt_pk_bf16_f32 v116, v174, v175
	ds_read_b64 v[174:175], v163
	v_bitop3_b32 v163, v3, v129, 8 bitop3:0x1e
	v_cvt_pk_bf16_f32 v117, v176, v177
	v_cvt_pk_bf16_f32 v118, v178, v179
	v_cvt_pk_bf16_f32 v119, v180, v181
	v_lshl_add_u32 v163, v163, 1, v151
	s_waitcnt lgkmcnt(0)
	v_mfma_f32_16x16x32_bf16 v[84:87], v[172:175], v[116:119], v[84:87]
	ds_read_b64 v[172:173], v163 offset:8448
	v_bitop3_b32 v163, v139, v129, 8 bitop3:0x1e
	v_lshl_add_u32 v163, v163, 1, v151
	ds_read_b64 v[174:175], v163 offset:8448
	v_bitop3_b32 v163, v3, v129, 16 bitop3:0x1e
	v_lshl_add_u32 v163, v163, 1, v151
	s_waitcnt lgkmcnt(0)
	v_mfma_f32_16x16x32_bf16 v[88:91], v[172:175], v[116:119], v[88:91]
	ds_read_b64 v[172:173], v163 offset:16896
	v_bitop3_b32 v163, v139, v129, 16 bitop3:0x1e
	v_lshl_add_u32 v163, v163, 1, v151
	ds_read_b64 v[174:175], v163 offset:16896
	v_bitop3_b32 v163, v3, v129, 24 bitop3:0x1e
	v_lshl_add_u32 v163, v163, 1, v151
	s_waitcnt lgkmcnt(0)
	v_mfma_f32_16x16x32_bf16 v[92:95], v[172:175], v[116:119], v[92:95]
	ds_read_b64 v[172:173], v163 offset:25344
	v_bitop3_b32 v163, v139, v129, 24 bitop3:0x1e
	v_lshl_add_u32 v163, v163, 1, v151
	ds_read_b64 v[174:175], v163 offset:25344
	v_bitop3_b32 v163, v3, v129, 32 bitop3:0x1e
	v_lshl_add_u32 v163, v163, 1, v151
	s_waitcnt lgkmcnt(0)
	v_mfma_f32_16x16x32_bf16 v[96:99], v[172:175], v[116:119], v[96:99]
	ds_read_b64 v[172:173], v163 offset:33792
	v_bitop3_b32 v163, v139, v129, 32 bitop3:0x1e
	v_lshl_add_u32 v163, v163, 1, v151
	ds_read_b64 v[174:175], v163 offset:33792
	v_bitop3_b32 v163, v3, v129, 40 bitop3:0x1e
	v_lshl_add_u32 v163, v163, 1, v151
	s_waitcnt lgkmcnt(0)
	v_mfma_f32_16x16x32_bf16 v[100:103], v[172:175], v[116:119], v[100:103]
	ds_read_b64 v[172:173], v163 offset:42240
	v_bitop3_b32 v163, v139, v129, 40 bitop3:0x1e
	v_lshl_add_u32 v163, v163, 1, v151
	ds_read_b64 v[174:175], v163 offset:42240
	v_bitop3_b32 v163, v3, v129, 48 bitop3:0x1e
	v_lshl_add_u32 v163, v163, 1, v151
	s_waitcnt lgkmcnt(0)
	v_mfma_f32_16x16x32_bf16 v[104:107], v[172:175], v[116:119], v[104:107]
	ds_read_b64 v[172:173], v163 offset:50688
	v_bitop3_b32 v163, v139, v129, 48 bitop3:0x1e
	v_lshl_add_u32 v163, v163, 1, v151
	ds_read_b64 v[174:175], v163 offset:50688
	v_bitop3_b32 v3, v3, v129, 56 bitop3:0x1e
	v_lshl_add_u32 v3, v3, 1, v151
	s_waitcnt lgkmcnt(0)
	v_mfma_f32_16x16x32_bf16 v[108:111], v[172:175], v[116:119], v[108:111]
	ds_read_b64 v[172:173], v3 offset:59136
	v_bitop3_b32 v3, v139, v129, 56 bitop3:0x1e
	v_lshl_add_u32 v3, v3, 1, v151
	ds_read_b64 v[174:175], v3 offset:59136
	v_bitop3_b32 v3, v1, s36, v150 bitop3:0x1e
	v_lshl_add_u32 v3, v3, 1, v151
	ds_read_b64 v[164:165], v3
	v_bitop3_b32 v3, v2, s36, v150 bitop3:0x1e
	v_lshl_add_u32 v3, v3, 1, v151
	s_waitcnt lgkmcnt(1)
	v_mfma_f32_16x16x32_bf16 v[112:115], v[172:175], v[116:119], v[112:115]
	v_cvt_pk_bf16_f32 v117, v166, v167
	ds_read_b64 v[166:167], v3
	v_bitop3_b32 v3, v1, v129, 8 bitop3:0x1e
	v_lshl_add_u32 v3, v3, 1, v151
	v_cvt_pk_bf16_f32 v118, v168, v169
	ds_read_b64 v[168:169], v3 offset:8448
	v_bitop3_b32 v3, v2, v129, 8 bitop3:0x1e
	v_lshl_add_u32 v3, v3, 1, v151
	v_cvt_pk_bf16_f32 v119, v170, v171
	ds_read_b64 v[170:171], v3 offset:8448
	v_bitop3_b32 v3, v1, v129, 16 bitop3:0x1e
	v_lshl_add_u32 v3, v3, 1, v151
	ds_read_b64 v[172:173], v3 offset:16896
	v_bitop3_b32 v3, v2, v129, 16 bitop3:0x1e
	v_lshl_add_u32 v3, v3, 1, v151
	ds_read_b64 v[174:175], v3 offset:16896
	v_bitop3_b32 v3, v1, v129, 24 bitop3:0x1e
	v_lshl_add_u32 v3, v3, 1, v151
	ds_read_b64 v[176:177], v3 offset:25344
	v_bitop3_b32 v3, v2, v129, 24 bitop3:0x1e
	v_lshl_add_u32 v3, v3, 1, v151
	ds_read_b64 v[178:179], v3 offset:25344
	v_bitop3_b32 v3, v1, v129, 32 bitop3:0x1e
	v_lshl_add_u32 v3, v3, 1, v151
	ds_read_b64 v[180:181], v3 offset:33792
	v_bitop3_b32 v3, v2, v129, 32 bitop3:0x1e
	v_lshl_add_u32 v3, v3, 1, v151
	ds_read_b64 v[182:183], v3 offset:33792
	v_bitop3_b32 v3, v1, v129, 40 bitop3:0x1e
	v_lshl_add_u32 v3, v3, 1, v151
	ds_read_b64 v[184:185], v3 offset:42240
	v_bitop3_b32 v3, v2, v129, 40 bitop3:0x1e
	v_lshl_add_u32 v3, v3, 1, v151
	ds_read_b64 v[186:187], v3 offset:42240
	v_bitop3_b32 v3, v1, v129, 48 bitop3:0x1e
	v_bitop3_b32 v1, v1, v129, 56 bitop3:0x1e
	v_lshl_add_u32 v3, v3, 1, v151
	v_lshl_add_u32 v1, v1, 1, v151
	ds_read_b64 v[188:189], v3 offset:50688
	ds_read_b64 v[192:193], v1 offset:59136
	v_bitop3_b32 v3, v2, v129, 48 bitop3:0x1e
	v_bitop3_b32 v1, v2, v129, 56 bitop3:0x1e
	v_lshl_add_u32 v3, v3, 1, v151
	v_lshl_add_u32 v1, v1, 1, v151
	ds_read_b64 v[190:191], v3 offset:50688
	ds_read_b64 v[194:195], v1 offset:59136
	v_cvt_pk_bf16_f32 v116, v130, v131
	v_cvt_pk_bf16_f32 v3, v127, v128
	v_cvt_pk_bf16_f32 v2, v125, v126
	s_waitcnt lgkmcnt(14)
	v_mfma_f32_16x16x32_bf16 v[84:87], v[164:167], v[116:119], v[84:87]
	v_mov_b32_e32 v1, v0
	s_waitcnt lgkmcnt(12)
	v_mfma_f32_16x16x32_bf16 v[88:91], v[168:171], v[116:119], v[88:91]
	s_waitcnt lgkmcnt(10)
	v_mfma_f32_16x16x32_bf16 v[92:95], v[172:175], v[116:119], v[92:95]
	s_waitcnt lgkmcnt(8)
	v_mfma_f32_16x16x32_bf16 v[96:99], v[176:179], v[116:119], v[96:99]
	s_waitcnt lgkmcnt(6)
	v_mfma_f32_16x16x32_bf16 v[100:103], v[180:183], v[116:119], v[100:103]
	s_waitcnt lgkmcnt(4)
	v_mfma_f32_16x16x32_bf16 v[104:107], v[184:187], v[116:119], v[104:107]
	s_waitcnt lgkmcnt(1)
	v_mfma_f32_16x16x32_bf16 v[108:111], v[188:191], v[116:119], v[108:111]
	s_waitcnt lgkmcnt(0)
	v_mfma_f32_16x16x32_bf16 v[112:115], v[192:195], v[116:119], v[112:115]
	v_bitop3_b32 v116, v121, s36, v150 bitop3:0x1e
	v_lshl_add_u32 v116, v116, 1, v151
	ds_read_b64 v[118:119], v116
	v_mov_b32_e32 v116, v166
	v_mov_b32_e32 v117, v167
	s_waitcnt lgkmcnt(0)
	s_nop 0
	v_mfma_f32_16x16x32_bf16 v[84:87], v[116:119], v[0:3], v[84:87]
	v_bitop3_b32 v116, v121, v129, 8 bitop3:0x1e
	v_lshl_add_u32 v116, v116, 1, v151
	ds_read_b64 v[118:119], v116 offset:8448
	v_mov_b32_e32 v116, v170
	v_mov_b32_e32 v117, v171
	s_waitcnt lgkmcnt(0)
	s_nop 0
	v_mfma_f32_16x16x32_bf16 v[88:91], v[116:119], v[0:3], v[88:91]
	v_bitop3_b32 v116, v121, v129, 16 bitop3:0x1e
	v_lshl_add_u32 v116, v116, 1, v151
	ds_read_b64 v[118:119], v116 offset:16896
	v_mov_b32_e32 v116, v174
	v_mov_b32_e32 v117, v175
	s_waitcnt lgkmcnt(0)
	s_nop 0
	v_mfma_f32_16x16x32_bf16 v[92:95], v[116:119], v[0:3], v[92:95]
	v_bitop3_b32 v116, v121, v129, 24 bitop3:0x1e
	v_lshl_add_u32 v116, v116, 1, v151
	ds_read_b64 v[118:119], v116 offset:25344
	v_mov_b32_e32 v116, v178
	v_mov_b32_e32 v117, v179
	s_waitcnt lgkmcnt(0)
	s_nop 0
	v_mfma_f32_16x16x32_bf16 v[96:99], v[116:119], v[0:3], v[96:99]
	v_bitop3_b32 v116, v121, v129, 32 bitop3:0x1e
	v_lshl_add_u32 v116, v116, 1, v151
	ds_read_b64 v[118:119], v116 offset:33792
	v_mov_b32_e32 v116, v182
	v_mov_b32_e32 v117, v183
	s_waitcnt lgkmcnt(0)
	s_nop 0
	v_mfma_f32_16x16x32_bf16 v[100:103], v[116:119], v[0:3], v[100:103]
	v_bitop3_b32 v116, v121, v129, 40 bitop3:0x1e
	v_lshl_add_u32 v116, v116, 1, v151
	ds_read_b64 v[118:119], v116 offset:42240
	v_mov_b32_e32 v116, v186
	v_mov_b32_e32 v117, v187
	s_waitcnt lgkmcnt(0)
	s_nop 0
	v_mfma_f32_16x16x32_bf16 v[104:107], v[116:119], v[0:3], v[104:107]
	v_bitop3_b32 v116, v121, v129, 48 bitop3:0x1e
	v_lshl_add_u32 v116, v116, 1, v151
	ds_read_b64 v[118:119], v116 offset:50688
	v_mov_b32_e32 v116, v190
	v_mov_b32_e32 v117, v191
	s_waitcnt lgkmcnt(0)
	s_nop 0
	v_mfma_f32_16x16x32_bf16 v[108:111], v[116:119], v[0:3], v[108:111]
	v_bitop3_b32 v116, v121, v129, 56 bitop3:0x1e
	v_lshl_add_u32 v116, v116, 1, v151
	ds_read_b64 v[118:119], v116 offset:59136
	v_mov_b32_e32 v116, v194
	v_mov_b32_e32 v117, v195
	v_ashrrev_i32_e32 v121, 31, v120
	s_waitcnt lgkmcnt(0)
	v_mfma_f32_16x16x32_bf16 v[112:115], v[116:119], v[0:3], v[112:115]
	v_add_f32_e32 v1, v123, v124
	v_div_scale_f32 v2, s[26:27], v1, v1, 1.0
	v_rcp_f32_e32 v3, v2
	s_lshl_b64 s[26:27], s[92:93], 14
	s_add_u32 s26, s26, s94
	s_addc_u32 s27, s27, s95
	v_fma_f32 v116, -v2, v3, 1.0
	v_fmac_f32_e32 v3, v116, v3
	v_div_scale_f32 v116, vcc, 1.0, v1, 1.0
	v_mul_f32_e32 v117, v116, v3
	v_fma_f32 v118, -v2, v117, v116
	v_fmac_f32_e32 v117, v118, v3
	v_fma_f32 v2, -v2, v117, v116
	v_div_fmas_f32 v2, v2, v3, v117
	v_div_fixup_f32 v116, v2, v1, 1.0
	v_lshl_add_u64 v[2:3], s[26:27], 0, v[120:121]
	v_lshlrev_b64 v[118:119], 10, v[2:3]
	v_lshl_add_u64 v[118:119], s[66:67], 0, v[118:119]
	s_lshl_b32 s40, s37, 8
	v_lshl_add_u64 v[118:119], v[118:119], 0, s[40:41]
	v_lshlrev_b32_e32 v120, 1, v136
	v_mov_b32_e32 v121, v0
	v_pk_mul_f32 v[84:85], v[116:117], v[84:85] op_sel_hi:[0,1]
	v_pk_mul_f32 v[86:87], v[116:117], v[86:87] op_sel_hi:[0,1]
	v_lshl_add_u64 v[118:119], v[118:119], 0, v[120:121]
	v_cvt_pk_bf16_f32 v84, v84, v85
	v_cvt_pk_bf16_f32 v85, v86, v87
	global_store_dwordx2 v[118:119], v[84:85], off
	v_pk_mul_f32 v[84:85], v[116:117], v[88:89] op_sel_hi:[0,1]
	v_pk_mul_f32 v[86:87], v[116:117], v[90:91] op_sel_hi:[0,1]
	v_cvt_pk_bf16_f32 v84, v84, v85
	v_cvt_pk_bf16_f32 v85, v86, v87
	global_store_dwordx2 v[118:119], v[84:85], off offset:32
	v_pk_mul_f32 v[84:85], v[116:117], v[92:93] op_sel_hi:[0,1]
	v_pk_mul_f32 v[86:87], v[116:117], v[94:95] op_sel_hi:[0,1]
	v_cvt_pk_bf16_f32 v84, v84, v85
	v_cvt_pk_bf16_f32 v85, v86, v87
	global_store_dwordx2 v[118:119], v[84:85], off offset:64
	v_pk_mul_f32 v[84:85], v[116:117], v[96:97] op_sel_hi:[0,1]
	v_pk_mul_f32 v[86:87], v[116:117], v[98:99] op_sel_hi:[0,1]
	v_cvt_pk_bf16_f32 v84, v84, v85
	v_cvt_pk_bf16_f32 v85, v86, v87
	global_store_dwordx2 v[118:119], v[84:85], off offset:96
	v_pk_mul_f32 v[84:85], v[116:117], v[100:101] op_sel_hi:[0,1]
	v_pk_mul_f32 v[86:87], v[116:117], v[102:103] op_sel_hi:[0,1]
	v_cvt_pk_bf16_f32 v84, v84, v85
	v_cvt_pk_bf16_f32 v85, v86, v87
	global_store_dwordx2 v[118:119], v[84:85], off offset:128
	v_pk_mul_f32 v[84:85], v[116:117], v[104:105] op_sel_hi:[0,1]
	v_pk_mul_f32 v[86:87], v[116:117], v[106:107] op_sel_hi:[0,1]
	v_cvt_pk_bf16_f32 v84, v84, v85
	v_cvt_pk_bf16_f32 v85, v86, v87
	global_store_dwordx2 v[118:119], v[84:85], off offset:160
	v_pk_mul_f32 v[84:85], v[116:117], v[108:109] op_sel_hi:[0,1]
	v_pk_mul_f32 v[86:87], v[116:117], v[110:111] op_sel_hi:[0,1]
	v_cvt_pk_bf16_f32 v84, v84, v85
	v_cvt_pk_bf16_f32 v85, v86, v87
	global_store_dwordx2 v[118:119], v[84:85], off offset:192
	v_pk_mul_f32 v[84:85], v[116:117], v[112:113] op_sel_hi:[0,1]
	v_pk_mul_f32 v[86:87], v[116:117], v[114:115] op_sel_hi:[0,1]
	v_cvt_pk_bf16_f32 v84, v84, v85
	v_cvt_pk_bf16_f32 v85, v86, v87
	global_store_dwordx2 v[118:119], v[84:85], off offset:224
	s_and_saveexec_b64 s[26:27], s[4:5]
	s_cbranch_execz .LBB0_524
	v_log_f32_e32 v1, v1
	v_lshl_add_u64 v[2:3], v[2:3], 4, s[90:91]
	s_lshl_b32 s40, s37, 2
	v_lshl_add_u64 v[2:3], v[2:3], 0, s[40:41]
	v_add_f32_e32 v1, v122, v1
	v_mul_f32_e32 v1, 0x3f317218, v1
	global_store_dword v[2:3], v1, off
	s_branch .LBB0_524
